# forget-prompt attention: QK^T K-fragment LDS reads pipelined through an 8-deep register ring (was read-wait-MFMA serialized on one buffer)
# speedup vs baseline: 1.0190x; 1.0148x over previous
.LBB0_484:
	s_waitcnt lgkmcnt(0)
	s_barrier
	s_cmp_gt_u32 s79, s76
	s_cbranch_scc1 .LBB0_493
	v_add_u32_e32 v2, s78, v235
	v_add_u32_e32 v3, v2, v236
	v_add_u32_e32 v5, v2, v237
	v_add_u32_e32 v2, v2, v238
	ds_read_b128 v[6:9], v3 offset:128
	ds_read_b128 v[10:13], v5 offset:128
	ds_read_b128 v[14:17], v3 offset:11392
	ds_read_b128 v[182:185], v2 offset:128
	ds_read_b128 v[186:189], v3
	ds_read_b128 v[190:193], v3 offset:32
	ds_read_b128 v[222:225], v3 offset:64
	ds_read_b128 v[228:231], v3 offset:96
	v_sub_f32_e32 v66, 0, v180
	v_mov_b32_e32 v67, v66
	v_mov_b32_e32 v68, v66
	v_mov_b32_e32 v69, v66
	v_mov_b32_e32 v70, v66
	v_mov_b32_e32 v71, v66
	v_mov_b32_e32 v72, v66
	v_mov_b32_e32 v73, v66
	v_mov_b32_e32 v74, v66
	v_mov_b32_e32 v75, v66
	v_mov_b32_e32 v76, v66
	v_mov_b32_e32 v77, v66
	v_mov_b32_e32 v78, v66
	v_mov_b32_e32 v79, v66
	v_mov_b32_e32 v80, v66
	v_mov_b32_e32 v81, v66
	s_cmp_lg_u32 s76, s79
	s_waitcnt lgkmcnt(7)
	v_mfma_f32_32x32x16_bf16 v[114:129], v[6:9], v[130:133], v[66:81]
	ds_read_b128 v[6:9], v5
	s_waitcnt lgkmcnt(7)
	v_mfma_f32_32x32x16_bf16 v[82:97], v[10:13], v[130:133], v[66:81]
	ds_read_b128 v[10:13], v5 offset:32
	s_waitcnt lgkmcnt(7)
	v_mfma_f32_32x32x16_bf16 v[98:113], v[14:17], v[130:133], v[66:81]
	ds_read_b128 v[14:17], v5 offset:64
	s_waitcnt lgkmcnt(7)
	v_mfma_f32_32x32x16_bf16 v[66:81], v[182:185], v[130:133], v[66:81]
	ds_read_b128 v[182:185], v5 offset:96
	s_waitcnt lgkmcnt(7)
	v_mfma_f32_32x32x16_bf16 v[114:129], v[186:189], v[142:145], v[114:129]
	ds_read_b128 v[186:189], v3 offset:11264
	s_waitcnt lgkmcnt(7)
	v_mfma_f32_32x32x16_bf16 v[114:129], v[190:193], v[146:149], v[114:129]
	ds_read_b128 v[190:193], v3 offset:11296
	s_waitcnt lgkmcnt(7)
	v_mfma_f32_32x32x16_bf16 v[114:129], v[222:225], v[150:153], v[114:129]
	ds_read_b128 v[222:225], v3 offset:11328
	s_waitcnt lgkmcnt(7)
	v_mfma_f32_32x32x16_bf16 v[114:129], v[228:231], v[154:157], v[114:129]
	ds_read_b128 v[228:231], v3 offset:11360
	s_waitcnt lgkmcnt(7)
	v_mfma_f32_32x32x16_bf16 v[82:97], v[6:9], v[142:145], v[82:97]
	ds_read_b128 v[6:9], v2
	s_waitcnt lgkmcnt(7)
	v_mfma_f32_32x32x16_bf16 v[82:97], v[10:13], v[146:149], v[82:97]
	ds_read_b128 v[10:13], v2 offset:32
	s_waitcnt lgkmcnt(7)
	v_mfma_f32_32x32x16_bf16 v[82:97], v[14:17], v[150:153], v[82:97]
	ds_read_b128 v[14:17], v2 offset:64
	s_waitcnt lgkmcnt(7)
	v_mfma_f32_32x32x16_bf16 v[82:97], v[182:185], v[154:157], v[82:97]
	ds_read_b128 v[182:185], v2 offset:96
	s_waitcnt lgkmcnt(7)
	v_mfma_f32_32x32x16_bf16 v[98:113], v[186:189], v[142:145], v[98:113]
	s_waitcnt lgkmcnt(6)
	v_mfma_f32_32x32x16_bf16 v[98:113], v[190:193], v[146:149], v[98:113]
	s_waitcnt lgkmcnt(5)
	v_mfma_f32_32x32x16_bf16 v[98:113], v[222:225], v[150:153], v[98:113]
	s_waitcnt lgkmcnt(4)
	v_mfma_f32_32x32x16_bf16 v[98:113], v[228:231], v[154:157], v[98:113]
	s_waitcnt lgkmcnt(3)
	v_mfma_f32_32x32x16_bf16 v[66:81], v[6:9], v[142:145], v[66:81]
	s_waitcnt lgkmcnt(2)
	v_mfma_f32_32x32x16_bf16 v[66:81], v[10:13], v[146:149], v[66:81]
	s_waitcnt lgkmcnt(1)
	v_mfma_f32_32x32x16_bf16 v[66:81], v[14:17], v[150:153], v[66:81]
	s_waitcnt lgkmcnt(0)
	v_mfma_f32_32x32x16_bf16 v[66:81], v[182:185], v[154:157], v[66:81]
	s_cbranch_scc1 .LBB0_487
	v_readlane_b32 s74, v254, 19
	v_readlane_b32 s75, v254, 20
	v_cndmask_b32_e64 v115, v197, v115, s[30:31]
	v_cndmask_b32_e64 v91, v91, v197, s[80:81]
	v_cndmask_b32_e64 v2, v114, v197, s[74:75]
	v_readlane_b32 s74, v254, 13
	v_readlane_b32 s75, v254, 14
	v_cndmask_b32_e64 v114, v2, v114, s[30:31]
	v_cndmask_b32_e64 v92, v92, v197, s[82:83]
	v_cndmask_b32_e64 v116, v116, v197, s[74:75]
	v_readlane_b32 s74, v254, 15
	v_readlane_b32 s75, v254, 16
	v_cndmask_b32_e64 v93, v93, v197, s[84:85]
	v_cndmask_b32_e64 v94, v94, v197, s[86:87]
	v_cndmask_b32_e64 v117, v117, v197, s[74:75]
	v_readlane_b32 s74, v254, 54
	v_readlane_b32 s75, v254, 55
	v_cndmask_b32_e64 v95, v95, v197, s[88:89]
	v_cndmask_b32_e64 v96, v96, v197, s[90:91]
	v_cndmask_b32_e64 v118, v118, v197, s[74:75]
	v_readlane_b32 s74, v254, 56
	v_readlane_b32 s75, v254, 57
	v_cndmask_b32_e64 v97, v97, v197, s[92:93]
	v_cndmask_b32_e64 v98, v98, v197, s[94:95]
	v_cndmask_b32_e64 v119, v119, v197, s[74:75]
	v_readlane_b32 s74, v254, 58
	v_readlane_b32 s75, v254, 59
	v_cndmask_b32_e64 v99, v99, v197, s[96:97]
	v_cndmask_b32_e64 v100, v100, v197, s[66:67]
	v_cndmask_b32_e64 v120, v120, v197, s[74:75]
	v_readlane_b32 s74, v254, 60
	v_readlane_b32 s75, v254, 61
	v_cndmask_b32_e64 v101, v101, v197, s[6:7]
	v_cndmask_b32_e64 v102, v102, v197, s[12:13]
	v_cndmask_b32_e64 v121, v121, v197, s[74:75]
	v_readlane_b32 s74, v254, 62
	v_readlane_b32 s75, v254, 63
	v_cndmask_b32_e64 v103, v103, v197, s[16:17]
	v_cndmask_b32_e64 v104, v104, v197, s[18:19]
	v_cndmask_b32_e64 v122, v122, v197, s[74:75]
	v_readlane_b32 s74, v255, 0
	v_readlane_b32 s75, v255, 1
	v_cndmask_b32_e64 v105, v105, v197, s[20:21]
	v_cndmask_b32_e64 v106, v106, v197, s[22:23]
	v_cndmask_b32_e64 v123, v123, v197, s[74:75]
	v_readlane_b32 s74, v255, 2
	v_readlane_b32 s75, v255, 3
	v_cndmask_b32_e64 v107, v107, v197, s[24:25]
	v_cndmask_b32_e64 v108, v108, v197, s[26:27]
	v_cndmask_b32_e64 v124, v124, v197, s[74:75]
	v_readlane_b32 s74, v255, 4
	v_readlane_b32 s75, v255, 5
	v_cndmask_b32_e64 v109, v109, v197, s[0:1]
	v_cndmask_b32_e64 v110, v110, v197, s[14:15]
	v_cndmask_b32_e64 v125, v125, v197, s[74:75]
	v_readlane_b32 s74, v255, 6
	v_readlane_b32 s75, v255, 7
	v_cndmask_b32_e64 v111, v111, v197, s[10:11]
	v_cndmask_b32_e64 v112, v112, v197, s[8:9]
	v_cndmask_b32_e64 v126, v126, v197, s[74:75]
	v_readlane_b32 s74, v255, 8
	v_readlane_b32 s75, v255, 9
	v_cndmask_b32_e64 v113, v113, v197, s[28:29]
	v_cndmask_b32_e64 v66, v66, v197, s[34:35]
	v_cndmask_b32_e64 v127, v127, v197, s[74:75]
	v_readlane_b32 s74, v255, 10
	v_readlane_b32 s75, v255, 11
	v_cndmask_b32_e64 v67, v67, v197, s[36:37]
	v_cndmask_b32_e64 v68, v68, v197, s[38:39]
	v_cndmask_b32_e64 v128, v128, v197, s[74:75]
	v_readlane_b32 s74, v255, 12
	v_readlane_b32 s75, v255, 13
	v_cndmask_b32_e64 v69, v69, v197, s[40:41]
	v_cndmask_b32_e64 v70, v70, v197, s[42:43]
	v_cndmask_b32_e64 v129, v129, v197, s[74:75]
	v_readlane_b32 s74, v255, 14
	v_readlane_b32 s75, v255, 15
	v_cndmask_b32_e64 v71, v71, v197, s[44:45]
	v_cndmask_b32_e64 v72, v72, v197, s[46:47]
	v_cndmask_b32_e64 v82, v82, v197, s[74:75]
	v_readlane_b32 s74, v255, 16
	v_readlane_b32 s75, v255, 17
	v_cndmask_b32_e64 v73, v73, v197, s[48:49]
	v_cndmask_b32_e64 v74, v74, v197, s[50:51]
	v_cndmask_b32_e64 v83, v83, v197, s[74:75]
	v_readlane_b32 s74, v255, 18
	v_readlane_b32 s75, v255, 19
	v_cndmask_b32_e64 v75, v75, v197, s[52:53]
	v_cndmask_b32_e64 v76, v76, v197, s[54:55]
	v_cndmask_b32_e64 v84, v84, v197, s[74:75]
	v_readlane_b32 s74, v255, 20
	v_readlane_b32 s75, v255, 21
	v_cndmask_b32_e64 v77, v77, v197, s[56:57]
	v_cndmask_b32_e64 v78, v78, v197, s[58:59]
	v_cndmask_b32_e64 v85, v85, v197, s[74:75]
	v_readlane_b32 s74, v255, 22
	v_readlane_b32 s75, v255, 23
	v_cndmask_b32_e64 v79, v79, v197, s[60:61]
	v_cndmask_b32_e64 v80, v80, v197, s[62:63]
	v_cndmask_b32_e64 v86, v86, v197, s[74:75]
	v_readlane_b32 s74, v255, 24
	v_readlane_b32 s75, v255, 25
	v_cndmask_b32_e64 v81, v81, v197, s[64:65]
	s_nop 0
	v_cndmask_b32_e64 v87, v87, v197, s[74:75]
	v_readlane_b32 s74, v255, 26
	v_readlane_b32 s75, v255, 27
	s_nop 1
	v_cndmask_b32_e64 v88, v88, v197, s[74:75]
	v_readlane_b32 s74, v255, 28
	v_readlane_b32 s75, v255, 29
	s_nop 1
	v_cndmask_b32_e64 v89, v89, v197, s[74:75]
	v_readlane_b32 s74, v255, 30
	v_readlane_b32 s75, v255, 31
	s_nop 1
	v_cndmask_b32_e64 v90, v90, v197, s[74:75]
